# baseline (speedup 1.0000x reference)
.LBB0_456:
	s_lshl_b32 s21, s26, 8
	s_add_i32 s21, s21, s85
	v_or_b32_e32 v146, s21, v149
	v_ashrrev_i32_e32 v147, 31, v146
	v_lshl_add_u64 v[142:143], v[146:147], 2, s[6:7]
	global_load_dwordx4 v[154:157], v[142:143], off
	s_lshl_b32 s19, s92, 9
	s_ashr_i32 s12, s21, 6
	s_add_i32 s12, s12, s19
	v_lshrrev_b32_e32 v132, 3, v146
	s_ashr_i32 s13, s12, 31
	s_add_i32 s28, s12, 0x100
	v_xor_b32_e32 v132, v132, v150
	s_lshl_b64 s[12:13], s[12:13], 14
	s_ashr_i32 s29, s28, 31
	v_lshlrev_b32_e32 v132, 4, v132
	v_lshl_add_u64 v[142:143], v[136:137], 0, s[12:13]
	s_lshl_b64 s[12:13], s[28:29], 14
	v_and_b32_e32 v132, 0x70, v132
	v_lshl_add_u64 v[144:145], v[136:137], 0, s[12:13]
	v_or_b32_e32 v158, 16, v146
	v_lshl_add_u64 v[162:163], v[142:143], 0, v[132:133]
	v_lshl_add_u64 v[164:165], v[144:145], 0, v[132:133]
	v_ashrrev_i32_e32 v159, 31, v158
	v_lshl_add_u64 v[162:163], v[162:163], 0, v[134:135]
	v_lshl_add_u64 v[164:165], v[164:165], 0, v[134:135]
	v_lshl_add_u64 v[160:161], v[158:159], 2, s[6:7]
	s_addk_i32 s21, 0x80
	s_ashr_i32 s12, s21, 6
	s_add_i32 s12, s12, s19
	s_ashr_i32 s13, s12, 31
	s_add_i32 s28, s12, 0x100
	s_lshl_b64 s[12:13], s[12:13], 14
	s_ashr_i32 s29, s28, 31
	s_andn2_b64 vcc, exec, s[4:5]
	s_mov_b64 s[4:5], -1
	s_waitcnt vmcnt(0)
	v_pk_mul_f32 v[124:125], v[124:125], v[154:155]
	v_pk_mul_f32 v[120:121], v[120:121], v[154:155]
	v_pk_mul_f32 v[116:117], v[116:117], v[154:155]
	v_pk_mul_f32 v[112:113], v[112:113], v[154:155]
	v_pk_mul_f32 v[126:127], v[126:127], v[156:157]
	v_pk_mul_f32 v[122:123], v[122:123], v[156:157]
	v_pk_mul_f32 v[118:119], v[118:119], v[156:157]
	v_pk_mul_f32 v[114:115], v[114:115], v[156:157]
	v_mbcnt_lo_u32_b32 v252, -1, 0
	v_mbcnt_hi_u32_b32 v252, -1, v252
	v_and_b32_e32 v252, 16, v252
	v_lshlrev_b32_e32 v253, 7, v252
	v_lshrrev_b32_e32 v252, 1, v252
	v_sub_u32_e32 v252, v253, v252
	v_mov_b32_e32 v253, 0
	v_cvt_pk_bf16_f32 v244, v124, v125
	v_cvt_pk_bf16_f32 v245, v126, v127
	s_nop 0
	v_cvt_pk_bf16_f32 v246, v120, v121
	v_cvt_pk_bf16_f32 v247, v122, v123
	s_nop 1
	v_permlane16_swap_b32_e32 v244, v246
	v_permlane16_swap_b32_e32 v245, v247
	v_lshl_add_u64 v[242:243], v[162:163], 0, v[252:253]
	global_store_dwordx4 v[242:243], v[244:247], off
	v_cvt_pk_bf16_f32 v248, v116, v117
	v_cvt_pk_bf16_f32 v249, v118, v119
	s_nop 0
	v_cvt_pk_bf16_f32 v250, v112, v113
	v_cvt_pk_bf16_f32 v251, v114, v115
	s_nop 1
	v_permlane16_swap_b32_e32 v248, v250
	v_permlane16_swap_b32_e32 v249, v251
	v_lshl_add_u64 v[242:243], v[164:165], 0, v[252:253]
	global_store_dwordx4 v[242:243], v[248:251], off
	global_load_dwordx4 v[112:115], v[160:161], off
	v_or_b32_e32 v116, 32, v146
	v_lshrrev_b32_e32 v118, 3, v158
	v_ashrrev_i32_e32 v117, 31, v116
	v_xor_b32_e32 v120, v118, v150
	v_lshl_add_u64 v[118:119], v[116:117], 2, s[6:7]
	v_lshlrev_b32_e32 v117, 4, v120
	v_and_b32_e32 v132, 0x70, v117
	v_lshl_add_u64 v[120:121], v[142:143], 0, v[132:133]
	v_lshl_add_u64 v[122:123], v[144:145], 0, v[132:133]
	v_lshl_add_u64 v[120:121], v[120:121], 0, v[134:135]
	v_lshl_add_u64 v[122:123], v[122:123], 0, v[134:135]
	s_waitcnt vmcnt(0)
	v_pk_mul_f32 v[108:109], v[108:109], v[112:113]
	v_pk_mul_f32 v[104:105], v[104:105], v[112:113]
	v_pk_mul_f32 v[100:101], v[100:101], v[112:113]
	v_pk_mul_f32 v[96:97], v[96:97], v[112:113]
	v_pk_mul_f32 v[110:111], v[110:111], v[114:115]
	v_pk_mul_f32 v[106:107], v[106:107], v[114:115]
	v_pk_mul_f32 v[102:103], v[102:103], v[114:115]
	v_pk_mul_f32 v[98:99], v[98:99], v[114:115]
	v_cvt_pk_bf16_f32 v244, v108, v109
	v_cvt_pk_bf16_f32 v245, v110, v111
	s_nop 0
	v_cvt_pk_bf16_f32 v246, v104, v105
	v_cvt_pk_bf16_f32 v247, v106, v107
	s_nop 1
	v_permlane16_swap_b32_e32 v244, v246
	v_permlane16_swap_b32_e32 v245, v247
	v_lshl_add_u64 v[242:243], v[120:121], 0, v[252:253]
	global_store_dwordx4 v[242:243], v[244:247], off
	v_cvt_pk_bf16_f32 v248, v100, v101
	v_cvt_pk_bf16_f32 v249, v102, v103
	s_nop 0
	v_cvt_pk_bf16_f32 v250, v96, v97
	v_cvt_pk_bf16_f32 v251, v98, v99
	s_nop 1
	v_permlane16_swap_b32_e32 v248, v250
	v_permlane16_swap_b32_e32 v249, v251
	v_lshl_add_u64 v[242:243], v[122:123], 0, v[252:253]
	global_store_dwordx4 v[242:243], v[248:251], off
	global_load_dwordx4 v[96:99], v[118:119], off
	v_or_b32_e32 v100, 48, v146
	v_lshrrev_b32_e32 v102, 3, v116
	v_ashrrev_i32_e32 v101, 31, v100
	v_xor_b32_e32 v104, v102, v150
	v_lshl_add_u64 v[102:103], v[100:101], 2, s[6:7]
	v_lshlrev_b32_e32 v101, 4, v104
	v_and_b32_e32 v132, 0x70, v101
	v_lshl_add_u64 v[104:105], v[142:143], 0, v[132:133]
	v_lshl_add_u64 v[106:107], v[144:145], 0, v[132:133]
	v_lshl_add_u64 v[104:105], v[104:105], 0, v[134:135]
	v_lshl_add_u64 v[106:107], v[106:107], 0, v[134:135]
	s_waitcnt vmcnt(0)
	v_pk_mul_f32 v[92:93], v[92:93], v[96:97]
	v_pk_mul_f32 v[88:89], v[88:89], v[96:97]
	v_pk_mul_f32 v[84:85], v[84:85], v[96:97]
	v_pk_mul_f32 v[80:81], v[80:81], v[96:97]
	v_pk_mul_f32 v[94:95], v[94:95], v[98:99]
	v_pk_mul_f32 v[90:91], v[90:91], v[98:99]
	v_pk_mul_f32 v[86:87], v[86:87], v[98:99]
	v_pk_mul_f32 v[82:83], v[82:83], v[98:99]
	v_cvt_pk_bf16_f32 v244, v92, v93
	v_cvt_pk_bf16_f32 v245, v94, v95
	s_nop 0
	v_cvt_pk_bf16_f32 v246, v88, v89
	v_cvt_pk_bf16_f32 v247, v90, v91
	s_nop 1
	v_permlane16_swap_b32_e32 v244, v246
	v_permlane16_swap_b32_e32 v245, v247
	v_lshl_add_u64 v[242:243], v[104:105], 0, v[252:253]
	global_store_dwordx4 v[242:243], v[244:247], off
	v_cvt_pk_bf16_f32 v248, v84, v85
	v_cvt_pk_bf16_f32 v249, v86, v87
	s_nop 0
	v_cvt_pk_bf16_f32 v250, v80, v81
	v_cvt_pk_bf16_f32 v251, v82, v83
	s_nop 1
	v_permlane16_swap_b32_e32 v248, v250
	v_permlane16_swap_b32_e32 v249, v251
	v_lshl_add_u64 v[242:243], v[106:107], 0, v[252:253]
	global_store_dwordx4 v[242:243], v[248:251], off
	global_load_dwordx4 v[82:85], v[102:103], off
	v_or_b32_e32 v80, s21, v149
	v_lshrrev_b32_e32 v86, 3, v100
	v_ashrrev_i32_e32 v81, 31, v80
	v_xor_b32_e32 v88, v86, v150
	v_lshl_add_u64 v[86:87], v[80:81], 2, s[6:7]
	v_lshlrev_b32_e32 v81, 4, v88
	v_and_b32_e32 v132, 0x70, v81
	v_lshl_add_u64 v[88:89], v[142:143], 0, v[132:133]
	v_lshl_add_u64 v[90:91], v[144:145], 0, v[132:133]
	v_lshl_add_u64 v[88:89], v[88:89], 0, v[134:135]
	v_lshl_add_u64 v[90:91], v[90:91], 0, v[134:135]
	s_waitcnt vmcnt(0)
	v_pk_mul_f32 v[76:77], v[76:77], v[82:83]
	v_pk_mul_f32 v[72:73], v[72:73], v[82:83]
	v_pk_mul_f32 v[68:69], v[68:69], v[82:83]
	v_pk_mul_f32 v[64:65], v[64:65], v[82:83]
	v_pk_mul_f32 v[78:79], v[78:79], v[84:85]
	v_pk_mul_f32 v[74:75], v[74:75], v[84:85]
	v_pk_mul_f32 v[70:71], v[70:71], v[84:85]
	v_pk_mul_f32 v[66:67], v[66:67], v[84:85]
	v_cvt_pk_bf16_f32 v244, v76, v77
	v_cvt_pk_bf16_f32 v245, v78, v79
	s_nop 0
	v_cvt_pk_bf16_f32 v246, v72, v73
	v_cvt_pk_bf16_f32 v247, v74, v75
	s_nop 1
	v_permlane16_swap_b32_e32 v244, v246
	v_permlane16_swap_b32_e32 v245, v247
	v_lshl_add_u64 v[242:243], v[88:89], 0, v[252:253]
	global_store_dwordx4 v[242:243], v[244:247], off
	v_cvt_pk_bf16_f32 v248, v68, v69
	v_cvt_pk_bf16_f32 v249, v70, v71
	s_nop 0
	v_cvt_pk_bf16_f32 v250, v64, v65
	v_cvt_pk_bf16_f32 v251, v66, v67
	s_nop 1
	v_permlane16_swap_b32_e32 v248, v250
	v_permlane16_swap_b32_e32 v249, v251
	v_lshl_add_u64 v[242:243], v[90:91], 0, v[252:253]
	global_store_dwordx4 v[242:243], v[248:251], off
	global_load_dwordx4 v[68:71], v[86:87], off
	v_lshrrev_b32_e32 v64, 3, v80
	v_xor_b32_e32 v64, v64, v150
	v_lshlrev_b32_e32 v76, 4, v64
	v_lshl_add_u64 v[64:65], v[136:137], 0, s[12:13]
	s_lshl_b64 s[12:13], s[28:29], 14
	v_lshl_add_u64 v[66:67], v[136:137], 0, s[12:13]
	v_and_b32_e32 v132, 0x70, v76
	v_or_b32_e32 v72, 16, v80
	v_lshl_add_u64 v[76:77], v[64:65], 0, v[132:133]
	v_lshl_add_u64 v[78:79], v[66:67], 0, v[132:133]
	v_ashrrev_i32_e32 v73, 31, v72
	v_lshl_add_u64 v[76:77], v[76:77], 0, v[134:135]
	v_lshl_add_u64 v[78:79], v[78:79], 0, v[134:135]
	v_lshl_add_u64 v[74:75], v[72:73], 2, s[6:7]
	s_waitcnt vmcnt(0)
	v_pk_mul_f32 v[60:61], v[60:61], v[68:69]
	v_pk_mul_f32 v[56:57], v[56:57], v[68:69]
	v_pk_mul_f32 v[52:53], v[52:53], v[68:69]
	v_pk_mul_f32 v[48:49], v[48:49], v[68:69]
	v_pk_mul_f32 v[62:63], v[62:63], v[70:71]
	v_pk_mul_f32 v[58:59], v[58:59], v[70:71]
	v_pk_mul_f32 v[54:55], v[54:55], v[70:71]
	v_pk_mul_f32 v[50:51], v[50:51], v[70:71]
	v_cvt_pk_bf16_f32 v244, v60, v61
	v_cvt_pk_bf16_f32 v245, v62, v63
	s_nop 0
	v_cvt_pk_bf16_f32 v246, v56, v57
	v_cvt_pk_bf16_f32 v247, v58, v59
	s_nop 1
	v_permlane16_swap_b32_e32 v244, v246
	v_permlane16_swap_b32_e32 v245, v247
	v_lshl_add_u64 v[242:243], v[76:77], 0, v[252:253]
	global_store_dwordx4 v[242:243], v[244:247], off
	v_cvt_pk_bf16_f32 v248, v52, v53
	v_cvt_pk_bf16_f32 v249, v54, v55
	s_nop 0
	v_cvt_pk_bf16_f32 v250, v48, v49
	v_cvt_pk_bf16_f32 v251, v50, v51
	s_nop 1
	v_permlane16_swap_b32_e32 v248, v250
	v_permlane16_swap_b32_e32 v249, v251
	v_lshl_add_u64 v[242:243], v[78:79], 0, v[252:253]
	global_store_dwordx4 v[242:243], v[248:251], off
	global_load_dwordx4 v[48:51], v[74:75], off
	v_or_b32_e32 v52, 32, v80
	v_lshrrev_b32_e32 v54, 3, v72
	v_ashrrev_i32_e32 v53, 31, v52
	v_xor_b32_e32 v56, v54, v150
	v_lshl_add_u64 v[54:55], v[52:53], 2, s[6:7]
	v_lshlrev_b32_e32 v53, 4, v56
	v_and_b32_e32 v132, 0x70, v53
	v_lshl_add_u64 v[56:57], v[64:65], 0, v[132:133]
	v_lshl_add_u64 v[58:59], v[66:67], 0, v[132:133]
	v_lshl_add_u64 v[56:57], v[56:57], 0, v[134:135]
	v_lshl_add_u64 v[58:59], v[58:59], 0, v[134:135]
	s_waitcnt vmcnt(0)
	v_pk_mul_f32 v[44:45], v[44:45], v[48:49]
	v_pk_mul_f32 v[40:41], v[40:41], v[48:49]
	v_pk_mul_f32 v[36:37], v[36:37], v[48:49]
	v_pk_mul_f32 v[32:33], v[32:33], v[48:49]
	v_pk_mul_f32 v[46:47], v[46:47], v[50:51]
	v_pk_mul_f32 v[42:43], v[42:43], v[50:51]
	v_pk_mul_f32 v[38:39], v[38:39], v[50:51]
	v_pk_mul_f32 v[34:35], v[34:35], v[50:51]
	v_cvt_pk_bf16_f32 v244, v44, v45
	v_cvt_pk_bf16_f32 v245, v46, v47
	s_nop 0
	v_cvt_pk_bf16_f32 v246, v40, v41
	v_cvt_pk_bf16_f32 v247, v42, v43
	s_nop 1
	v_permlane16_swap_b32_e32 v244, v246
	v_permlane16_swap_b32_e32 v245, v247
	v_lshl_add_u64 v[242:243], v[56:57], 0, v[252:253]
	global_store_dwordx4 v[242:243], v[244:247], off
	v_cvt_pk_bf16_f32 v248, v36, v37
	v_cvt_pk_bf16_f32 v249, v38, v39
	s_nop 0
	v_cvt_pk_bf16_f32 v250, v32, v33
	v_cvt_pk_bf16_f32 v251, v34, v35
	s_nop 1
	v_permlane16_swap_b32_e32 v248, v250
	v_permlane16_swap_b32_e32 v249, v251
	v_lshl_add_u64 v[242:243], v[58:59], 0, v[252:253]
	global_store_dwordx4 v[242:243], v[248:251], off
	global_load_dwordx4 v[32:35], v[54:55], off
	v_or_b32_e32 v36, 48, v80
	v_lshrrev_b32_e32 v38, 3, v52
	v_ashrrev_i32_e32 v37, 31, v36
	v_xor_b32_e32 v40, v38, v150
	v_lshl_add_u64 v[38:39], v[36:37], 2, s[6:7]
	v_lshlrev_b32_e32 v37, 4, v40
	v_and_b32_e32 v132, 0x70, v37
	v_lshl_add_u64 v[40:41], v[64:65], 0, v[132:133]
	v_lshl_add_u64 v[42:43], v[66:67], 0, v[132:133]
	v_lshl_add_u64 v[40:41], v[40:41], 0, v[134:135]
	v_lshl_add_u64 v[42:43], v[42:43], 0, v[134:135]
	s_waitcnt vmcnt(0)
	v_pk_mul_f32 v[28:29], v[28:29], v[32:33]
	v_pk_mul_f32 v[24:25], v[24:25], v[32:33]
	v_pk_mul_f32 v[20:21], v[20:21], v[32:33]
	v_pk_mul_f32 v[16:17], v[16:17], v[32:33]
	v_pk_mul_f32 v[30:31], v[30:31], v[34:35]
	v_pk_mul_f32 v[26:27], v[26:27], v[34:35]
	v_pk_mul_f32 v[22:23], v[22:23], v[34:35]
	v_pk_mul_f32 v[18:19], v[18:19], v[34:35]
	v_cvt_pk_bf16_f32 v244, v28, v29
	v_cvt_pk_bf16_f32 v245, v30, v31
	s_nop 0
	v_cvt_pk_bf16_f32 v246, v24, v25
	v_cvt_pk_bf16_f32 v247, v26, v27
	s_nop 1
	v_permlane16_swap_b32_e32 v244, v246
	v_permlane16_swap_b32_e32 v245, v247
	v_lshl_add_u64 v[242:243], v[40:41], 0, v[252:253]
	global_store_dwordx4 v[242:243], v[244:247], off
	v_cvt_pk_bf16_f32 v248, v20, v21
	v_cvt_pk_bf16_f32 v249, v22, v23
	s_nop 0
	v_cvt_pk_bf16_f32 v250, v16, v17
	v_cvt_pk_bf16_f32 v251, v18, v19
	s_nop 1
	v_permlane16_swap_b32_e32 v248, v250
	v_permlane16_swap_b32_e32 v249, v251
	v_lshl_add_u64 v[242:243], v[42:43], 0, v[252:253]
	global_store_dwordx4 v[242:243], v[248:251], off
	global_load_dwordx4 v[16:19], v[38:39], off
	v_lshrrev_b32_e32 v20, 3, v36
	v_xor_b32_e32 v20, v20, v150
	v_lshlrev_b32_e32 v20, 4, v20
	v_and_b32_e32 v132, 0x70, v20
	v_lshl_add_u64 v[20:21], v[64:65], 0, v[132:133]
	v_lshl_add_u64 v[22:23], v[66:67], 0, v[132:133]
	v_lshl_add_u64 v[20:21], v[20:21], 0, v[134:135]
	v_lshl_add_u64 v[22:23], v[22:23], 0, v[134:135]
	s_waitcnt vmcnt(0)
	v_pk_mul_f32 v[12:13], v[12:13], v[16:17]
	v_pk_mul_f32 v[8:9], v[8:9], v[16:17]
	v_pk_mul_f32 v[4:5], v[4:5], v[16:17]
	v_pk_mul_f32 v[0:1], v[0:1], v[16:17]
	v_pk_mul_f32 v[14:15], v[14:15], v[18:19]
	v_pk_mul_f32 v[10:11], v[10:11], v[18:19]
	v_pk_mul_f32 v[6:7], v[6:7], v[18:19]
	v_pk_mul_f32 v[2:3], v[2:3], v[18:19]
	v_cvt_pk_bf16_f32 v244, v12, v13
	v_cvt_pk_bf16_f32 v245, v14, v15
	s_nop 0
	v_cvt_pk_bf16_f32 v246, v8, v9
	v_cvt_pk_bf16_f32 v247, v10, v11
	s_nop 1
	v_permlane16_swap_b32_e32 v244, v246
	v_permlane16_swap_b32_e32 v245, v247
	v_lshl_add_u64 v[242:243], v[20:21], 0, v[252:253]
	global_store_dwordx4 v[242:243], v[244:247], off
	v_cvt_pk_bf16_f32 v248, v4, v5
	v_cvt_pk_bf16_f32 v249, v6, v7
	s_nop 0
	v_cvt_pk_bf16_f32 v250, v0, v1
	v_cvt_pk_bf16_f32 v251, v2, v3
	s_nop 1
	v_permlane16_swap_b32_e32 v248, v250
	v_permlane16_swap_b32_e32 v249, v251
	v_lshl_add_u64 v[242:243], v[22:23], 0, v[252:253]
	global_store_dwordx4 v[242:243], v[248:251], off
	s_cbranch_vccnz .LBB0_445
	s_andn2_b64 vcc, exec, s[8:9]
	s_cbranch_vccnz .LBB0_444
	s_barrier
	s_branch .LBB0_444

.LBB0_1233:
	s_lshl_b32 s25, s30, 8
	s_add_i32 s25, s25, s51
	v_or_b32_e32 v150, s25, v154
	v_ashrrev_i32_e32 v151, 31, v150
	v_lshl_add_u64 v[146:147], v[150:151], 2, s[66:67]
	global_load_dwordx4 v[160:163], v[146:147], off
	s_lshl_b32 s23, s74, 9
	s_ashr_i32 s12, s25, 6
	s_add_i32 s12, s12, s23
	v_lshrrev_b32_e32 v132, 3, v150
	s_ashr_i32 s13, s12, 31
	s_add_i32 s36, s12, 0x100
	v_xor_b32_e32 v132, v132, v155
	s_lshl_b64 s[12:13], s[12:13], 14
	s_ashr_i32 s37, s36, 31
	v_lshlrev_b32_e32 v132, 4, v132
	v_lshl_add_u64 v[146:147], v[136:137], 0, s[12:13]
	s_lshl_b64 s[12:13], s[36:37], 14
	v_and_b32_e32 v132, 0x70, v132
	v_lshl_add_u64 v[148:149], v[136:137], 0, s[12:13]
	v_or_b32_e32 v164, 16, v150
	v_lshl_add_u64 v[168:169], v[146:147], 0, v[132:133]
	v_lshl_add_u64 v[170:171], v[148:149], 0, v[132:133]
	v_ashrrev_i32_e32 v165, 31, v164
	v_lshl_add_u64 v[168:169], v[168:169], 0, v[134:135]
	v_lshl_add_u64 v[170:171], v[170:171], 0, v[134:135]
	v_lshl_add_u64 v[166:167], v[164:165], 2, s[66:67]
	s_addk_i32 s25, 0x80
	s_ashr_i32 s12, s25, 6
	s_add_i32 s12, s12, s23
	s_ashr_i32 s13, s12, 31
	s_add_i32 s36, s12, 0x100
	s_lshl_b64 s[12:13], s[12:13], 14
	s_ashr_i32 s37, s36, 31
	s_andn2_b64 vcc, exec, s[4:5]
	s_mov_b64 s[4:5], -1
	s_waitcnt vmcnt(0)
	v_pk_mul_f32 v[124:125], v[124:125], v[160:161]
	v_pk_mul_f32 v[120:121], v[120:121], v[160:161]
	v_pk_mul_f32 v[116:117], v[116:117], v[160:161]
	v_pk_mul_f32 v[112:113], v[112:113], v[160:161]
	v_pk_mul_f32 v[126:127], v[126:127], v[162:163]
	v_pk_mul_f32 v[122:123], v[122:123], v[162:163]
	v_pk_mul_f32 v[118:119], v[118:119], v[162:163]
	v_pk_mul_f32 v[114:115], v[114:115], v[162:163]
	v_mbcnt_lo_u32_b32 v252, -1, 0
	v_mbcnt_hi_u32_b32 v252, -1, v252
	v_and_b32_e32 v252, 16, v252
	v_lshlrev_b32_e32 v253, 7, v252
	v_lshrrev_b32_e32 v252, 1, v252
	v_sub_u32_e32 v252, v253, v252
	v_mov_b32_e32 v253, 0
	v_cvt_pk_bf16_f32 v244, v124, v125
	v_cvt_pk_bf16_f32 v245, v126, v127
	s_nop 0
	v_cvt_pk_bf16_f32 v246, v120, v121
	v_cvt_pk_bf16_f32 v247, v122, v123
	s_nop 1
	v_permlane16_swap_b32_e32 v244, v246
	v_permlane16_swap_b32_e32 v245, v247
	v_lshl_add_u64 v[242:243], v[168:169], 0, v[252:253]
	global_store_dwordx4 v[242:243], v[244:247], off
	v_cvt_pk_bf16_f32 v248, v116, v117
	v_cvt_pk_bf16_f32 v249, v118, v119
	s_nop 0
	v_cvt_pk_bf16_f32 v250, v112, v113
	v_cvt_pk_bf16_f32 v251, v114, v115
	s_nop 1
	v_permlane16_swap_b32_e32 v248, v250
	v_permlane16_swap_b32_e32 v249, v251
	v_lshl_add_u64 v[242:243], v[170:171], 0, v[252:253]
	global_store_dwordx4 v[242:243], v[248:251], off
	global_load_dwordx4 v[112:115], v[166:167], off
	v_or_b32_e32 v116, 32, v150
	v_lshrrev_b32_e32 v118, 3, v164
	v_ashrrev_i32_e32 v117, 31, v116
	v_xor_b32_e32 v120, v118, v155
	v_lshl_add_u64 v[118:119], v[116:117], 2, s[66:67]
	v_lshlrev_b32_e32 v117, 4, v120
	v_and_b32_e32 v132, 0x70, v117
	v_lshl_add_u64 v[120:121], v[146:147], 0, v[132:133]
	v_lshl_add_u64 v[122:123], v[148:149], 0, v[132:133]
	v_lshl_add_u64 v[120:121], v[120:121], 0, v[134:135]
	v_lshl_add_u64 v[122:123], v[122:123], 0, v[134:135]
	s_waitcnt vmcnt(0)
	v_pk_mul_f32 v[108:109], v[108:109], v[112:113]
	v_pk_mul_f32 v[104:105], v[104:105], v[112:113]
	v_pk_mul_f32 v[100:101], v[100:101], v[112:113]
	v_pk_mul_f32 v[96:97], v[96:97], v[112:113]
	v_pk_mul_f32 v[110:111], v[110:111], v[114:115]
	v_pk_mul_f32 v[106:107], v[106:107], v[114:115]
	v_pk_mul_f32 v[102:103], v[102:103], v[114:115]
	v_pk_mul_f32 v[98:99], v[98:99], v[114:115]
	v_cvt_pk_bf16_f32 v244, v108, v109
	v_cvt_pk_bf16_f32 v245, v110, v111
	s_nop 0
	v_cvt_pk_bf16_f32 v246, v104, v105
	v_cvt_pk_bf16_f32 v247, v106, v107
	s_nop 1
	v_permlane16_swap_b32_e32 v244, v246
	v_permlane16_swap_b32_e32 v245, v247
	v_lshl_add_u64 v[242:243], v[120:121], 0, v[252:253]
	global_store_dwordx4 v[242:243], v[244:247], off
	v_cvt_pk_bf16_f32 v248, v100, v101
	v_cvt_pk_bf16_f32 v249, v102, v103
	s_nop 0
	v_cvt_pk_bf16_f32 v250, v96, v97
	v_cvt_pk_bf16_f32 v251, v98, v99
	s_nop 1
	v_permlane16_swap_b32_e32 v248, v250
	v_permlane16_swap_b32_e32 v249, v251
	v_lshl_add_u64 v[242:243], v[122:123], 0, v[252:253]
	global_store_dwordx4 v[242:243], v[248:251], off
	global_load_dwordx4 v[96:99], v[118:119], off
	v_or_b32_e32 v100, 48, v150
	v_lshrrev_b32_e32 v102, 3, v116
	v_ashrrev_i32_e32 v101, 31, v100
	v_xor_b32_e32 v104, v102, v155
	v_lshl_add_u64 v[102:103], v[100:101], 2, s[66:67]
	v_lshlrev_b32_e32 v101, 4, v104
	v_and_b32_e32 v132, 0x70, v101
	v_lshl_add_u64 v[104:105], v[146:147], 0, v[132:133]
	v_lshl_add_u64 v[106:107], v[148:149], 0, v[132:133]
	v_lshl_add_u64 v[104:105], v[104:105], 0, v[134:135]
	v_lshl_add_u64 v[106:107], v[106:107], 0, v[134:135]
	s_waitcnt vmcnt(0)
	v_pk_mul_f32 v[92:93], v[92:93], v[96:97]
	v_pk_mul_f32 v[88:89], v[88:89], v[96:97]
	v_pk_mul_f32 v[84:85], v[84:85], v[96:97]
	v_pk_mul_f32 v[80:81], v[80:81], v[96:97]
	v_pk_mul_f32 v[94:95], v[94:95], v[98:99]
	v_pk_mul_f32 v[90:91], v[90:91], v[98:99]
	v_pk_mul_f32 v[86:87], v[86:87], v[98:99]
	v_pk_mul_f32 v[82:83], v[82:83], v[98:99]
	v_cvt_pk_bf16_f32 v244, v92, v93
	v_cvt_pk_bf16_f32 v245, v94, v95
	s_nop 0
	v_cvt_pk_bf16_f32 v246, v88, v89
	v_cvt_pk_bf16_f32 v247, v90, v91
	s_nop 1
	v_permlane16_swap_b32_e32 v244, v246
	v_permlane16_swap_b32_e32 v245, v247
	v_lshl_add_u64 v[242:243], v[104:105], 0, v[252:253]
	global_store_dwordx4 v[242:243], v[244:247], off
	v_cvt_pk_bf16_f32 v248, v84, v85
	v_cvt_pk_bf16_f32 v249, v86, v87
	s_nop 0
	v_cvt_pk_bf16_f32 v250, v80, v81
	v_cvt_pk_bf16_f32 v251, v82, v83
	s_nop 1
	v_permlane16_swap_b32_e32 v248, v250
	v_permlane16_swap_b32_e32 v249, v251
	v_lshl_add_u64 v[242:243], v[106:107], 0, v[252:253]
	global_store_dwordx4 v[242:243], v[248:251], off
	global_load_dwordx4 v[82:85], v[102:103], off
	v_or_b32_e32 v80, s25, v154
	v_lshrrev_b32_e32 v86, 3, v100
	v_ashrrev_i32_e32 v81, 31, v80
	v_xor_b32_e32 v88, v86, v155
	v_lshl_add_u64 v[86:87], v[80:81], 2, s[66:67]
	v_lshlrev_b32_e32 v81, 4, v88
	v_and_b32_e32 v132, 0x70, v81
	v_lshl_add_u64 v[88:89], v[146:147], 0, v[132:133]
	v_lshl_add_u64 v[90:91], v[148:149], 0, v[132:133]
	v_lshl_add_u64 v[88:89], v[88:89], 0, v[134:135]
	v_lshl_add_u64 v[90:91], v[90:91], 0, v[134:135]
	s_waitcnt vmcnt(0)
	v_pk_mul_f32 v[76:77], v[76:77], v[82:83]
	v_pk_mul_f32 v[72:73], v[72:73], v[82:83]
	v_pk_mul_f32 v[68:69], v[68:69], v[82:83]
	v_pk_mul_f32 v[64:65], v[64:65], v[82:83]
	v_pk_mul_f32 v[78:79], v[78:79], v[84:85]
	v_pk_mul_f32 v[74:75], v[74:75], v[84:85]
	v_pk_mul_f32 v[70:71], v[70:71], v[84:85]
	v_pk_mul_f32 v[66:67], v[66:67], v[84:85]
	v_cvt_pk_bf16_f32 v244, v76, v77
	v_cvt_pk_bf16_f32 v245, v78, v79
	s_nop 0
	v_cvt_pk_bf16_f32 v246, v72, v73
	v_cvt_pk_bf16_f32 v247, v74, v75
	s_nop 1
	v_permlane16_swap_b32_e32 v244, v246
	v_permlane16_swap_b32_e32 v245, v247
	v_lshl_add_u64 v[242:243], v[88:89], 0, v[252:253]
	global_store_dwordx4 v[242:243], v[244:247], off
	v_cvt_pk_bf16_f32 v248, v68, v69
	v_cvt_pk_bf16_f32 v249, v70, v71
	s_nop 0
	v_cvt_pk_bf16_f32 v250, v64, v65
	v_cvt_pk_bf16_f32 v251, v66, v67
	s_nop 1
	v_permlane16_swap_b32_e32 v248, v250
	v_permlane16_swap_b32_e32 v249, v251
	v_lshl_add_u64 v[242:243], v[90:91], 0, v[252:253]
	global_store_dwordx4 v[242:243], v[248:251], off
	global_load_dwordx4 v[68:71], v[86:87], off
	v_lshrrev_b32_e32 v64, 3, v80
	v_xor_b32_e32 v64, v64, v155
	v_lshlrev_b32_e32 v76, 4, v64
	v_lshl_add_u64 v[64:65], v[136:137], 0, s[12:13]
	s_lshl_b64 s[12:13], s[36:37], 14
	v_lshl_add_u64 v[66:67], v[136:137], 0, s[12:13]
	v_and_b32_e32 v132, 0x70, v76
	v_or_b32_e32 v72, 16, v80
	v_lshl_add_u64 v[76:77], v[64:65], 0, v[132:133]
	v_lshl_add_u64 v[78:79], v[66:67], 0, v[132:133]
	v_ashrrev_i32_e32 v73, 31, v72
	v_lshl_add_u64 v[76:77], v[76:77], 0, v[134:135]
	v_lshl_add_u64 v[78:79], v[78:79], 0, v[134:135]
	v_lshl_add_u64 v[74:75], v[72:73], 2, s[66:67]
	s_waitcnt vmcnt(0)
	v_pk_mul_f32 v[60:61], v[60:61], v[68:69]
	v_pk_mul_f32 v[56:57], v[56:57], v[68:69]
	v_pk_mul_f32 v[52:53], v[52:53], v[68:69]
	v_pk_mul_f32 v[48:49], v[48:49], v[68:69]
	v_pk_mul_f32 v[62:63], v[62:63], v[70:71]
	v_pk_mul_f32 v[58:59], v[58:59], v[70:71]
	v_pk_mul_f32 v[54:55], v[54:55], v[70:71]
	v_pk_mul_f32 v[50:51], v[50:51], v[70:71]
	v_cvt_pk_bf16_f32 v244, v60, v61
	v_cvt_pk_bf16_f32 v245, v62, v63
	s_nop 0
	v_cvt_pk_bf16_f32 v246, v56, v57
	v_cvt_pk_bf16_f32 v247, v58, v59
	s_nop 1
	v_permlane16_swap_b32_e32 v244, v246
	v_permlane16_swap_b32_e32 v245, v247
	v_lshl_add_u64 v[242:243], v[76:77], 0, v[252:253]
	global_store_dwordx4 v[242:243], v[244:247], off
	v_cvt_pk_bf16_f32 v248, v52, v53
	v_cvt_pk_bf16_f32 v249, v54, v55
	s_nop 0
	v_cvt_pk_bf16_f32 v250, v48, v49
	v_cvt_pk_bf16_f32 v251, v50, v51
	s_nop 1
	v_permlane16_swap_b32_e32 v248, v250
	v_permlane16_swap_b32_e32 v249, v251
	v_lshl_add_u64 v[242:243], v[78:79], 0, v[252:253]
	global_store_dwordx4 v[242:243], v[248:251], off
	global_load_dwordx4 v[48:51], v[74:75], off
	v_or_b32_e32 v52, 32, v80
	v_lshrrev_b32_e32 v54, 3, v72
	v_ashrrev_i32_e32 v53, 31, v52
	v_xor_b32_e32 v56, v54, v155
	v_lshl_add_u64 v[54:55], v[52:53], 2, s[66:67]
	v_lshlrev_b32_e32 v53, 4, v56
	v_and_b32_e32 v132, 0x70, v53
	v_lshl_add_u64 v[56:57], v[64:65], 0, v[132:133]
	v_lshl_add_u64 v[58:59], v[66:67], 0, v[132:133]
	v_lshl_add_u64 v[56:57], v[56:57], 0, v[134:135]
	v_lshl_add_u64 v[58:59], v[58:59], 0, v[134:135]
	s_waitcnt vmcnt(0)
	v_pk_mul_f32 v[44:45], v[44:45], v[48:49]
	v_pk_mul_f32 v[40:41], v[40:41], v[48:49]
	v_pk_mul_f32 v[36:37], v[36:37], v[48:49]
	v_pk_mul_f32 v[32:33], v[32:33], v[48:49]
	v_pk_mul_f32 v[46:47], v[46:47], v[50:51]
	v_pk_mul_f32 v[42:43], v[42:43], v[50:51]
	v_pk_mul_f32 v[38:39], v[38:39], v[50:51]
	v_pk_mul_f32 v[34:35], v[34:35], v[50:51]
	v_cvt_pk_bf16_f32 v244, v44, v45
	v_cvt_pk_bf16_f32 v245, v46, v47
	s_nop 0
	v_cvt_pk_bf16_f32 v246, v40, v41
	v_cvt_pk_bf16_f32 v247, v42, v43
	s_nop 1
	v_permlane16_swap_b32_e32 v244, v246
	v_permlane16_swap_b32_e32 v245, v247
	v_lshl_add_u64 v[242:243], v[56:57], 0, v[252:253]
	global_store_dwordx4 v[242:243], v[244:247], off
	v_cvt_pk_bf16_f32 v248, v36, v37
	v_cvt_pk_bf16_f32 v249, v38, v39
	s_nop 0
	v_cvt_pk_bf16_f32 v250, v32, v33
	v_cvt_pk_bf16_f32 v251, v34, v35
	s_nop 1
	v_permlane16_swap_b32_e32 v248, v250
	v_permlane16_swap_b32_e32 v249, v251
	v_lshl_add_u64 v[242:243], v[58:59], 0, v[252:253]
	global_store_dwordx4 v[242:243], v[248:251], off
	global_load_dwordx4 v[32:35], v[54:55], off
	v_or_b32_e32 v36, 48, v80
	v_lshrrev_b32_e32 v38, 3, v52
	v_ashrrev_i32_e32 v37, 31, v36
	v_xor_b32_e32 v40, v38, v155
	v_lshl_add_u64 v[38:39], v[36:37], 2, s[66:67]
	v_lshlrev_b32_e32 v37, 4, v40
	v_and_b32_e32 v132, 0x70, v37
	v_lshl_add_u64 v[40:41], v[64:65], 0, v[132:133]
	v_lshl_add_u64 v[42:43], v[66:67], 0, v[132:133]
	v_lshl_add_u64 v[40:41], v[40:41], 0, v[134:135]
	v_lshl_add_u64 v[42:43], v[42:43], 0, v[134:135]
	s_waitcnt vmcnt(0)
	v_pk_mul_f32 v[28:29], v[28:29], v[32:33]
	v_pk_mul_f32 v[24:25], v[24:25], v[32:33]
	v_pk_mul_f32 v[20:21], v[20:21], v[32:33]
	v_pk_mul_f32 v[16:17], v[16:17], v[32:33]
	v_pk_mul_f32 v[30:31], v[30:31], v[34:35]
	v_pk_mul_f32 v[26:27], v[26:27], v[34:35]
	v_pk_mul_f32 v[22:23], v[22:23], v[34:35]
	v_pk_mul_f32 v[18:19], v[18:19], v[34:35]
	v_cvt_pk_bf16_f32 v244, v28, v29
	v_cvt_pk_bf16_f32 v245, v30, v31
	s_nop 0
	v_cvt_pk_bf16_f32 v246, v24, v25
	v_cvt_pk_bf16_f32 v247, v26, v27
	s_nop 1
	v_permlane16_swap_b32_e32 v244, v246
	v_permlane16_swap_b32_e32 v245, v247
	v_lshl_add_u64 v[242:243], v[40:41], 0, v[252:253]
	global_store_dwordx4 v[242:243], v[244:247], off
	v_cvt_pk_bf16_f32 v248, v20, v21
	v_cvt_pk_bf16_f32 v249, v22, v23
	s_nop 0
	v_cvt_pk_bf16_f32 v250, v16, v17
	v_cvt_pk_bf16_f32 v251, v18, v19
	s_nop 1
	v_permlane16_swap_b32_e32 v248, v250
	v_permlane16_swap_b32_e32 v249, v251
	v_lshl_add_u64 v[242:243], v[42:43], 0, v[252:253]
	global_store_dwordx4 v[242:243], v[248:251], off
	global_load_dwordx4 v[16:19], v[38:39], off
	v_lshrrev_b32_e32 v20, 3, v36
	v_xor_b32_e32 v20, v20, v155
	v_lshlrev_b32_e32 v20, 4, v20
	v_and_b32_e32 v132, 0x70, v20
	v_lshl_add_u64 v[20:21], v[64:65], 0, v[132:133]
	v_lshl_add_u64 v[22:23], v[66:67], 0, v[132:133]
	v_lshl_add_u64 v[20:21], v[20:21], 0, v[134:135]
	v_lshl_add_u64 v[22:23], v[22:23], 0, v[134:135]
	s_waitcnt vmcnt(0)
	v_pk_mul_f32 v[12:13], v[12:13], v[16:17]
	v_pk_mul_f32 v[8:9], v[8:9], v[16:17]
	v_pk_mul_f32 v[4:5], v[4:5], v[16:17]
	v_pk_mul_f32 v[0:1], v[0:1], v[16:17]
	v_pk_mul_f32 v[14:15], v[14:15], v[18:19]
	v_pk_mul_f32 v[10:11], v[10:11], v[18:19]
	v_pk_mul_f32 v[6:7], v[6:7], v[18:19]
	v_pk_mul_f32 v[2:3], v[2:3], v[18:19]
	v_cvt_pk_bf16_f32 v244, v12, v13
	v_cvt_pk_bf16_f32 v245, v14, v15
	s_nop 0
	v_cvt_pk_bf16_f32 v246, v8, v9
	v_cvt_pk_bf16_f32 v247, v10, v11
	s_nop 1
	v_permlane16_swap_b32_e32 v244, v246
	v_permlane16_swap_b32_e32 v245, v247
	v_lshl_add_u64 v[242:243], v[20:21], 0, v[252:253]
	global_store_dwordx4 v[242:243], v[244:247], off
	v_cvt_pk_bf16_f32 v248, v4, v5
	v_cvt_pk_bf16_f32 v249, v6, v7
	s_nop 0
	v_cvt_pk_bf16_f32 v250, v0, v1
	v_cvt_pk_bf16_f32 v251, v2, v3
	s_nop 1
	v_permlane16_swap_b32_e32 v248, v250
	v_permlane16_swap_b32_e32 v249, v251
	v_lshl_add_u64 v[242:243], v[22:23], 0, v[252:253]
	global_store_dwordx4 v[242:243], v[248:251], off
	s_cbranch_vccnz .LBB0_1222
	s_andn2_b64 vcc, exec, s[6:7]
	s_cbranch_vccnz .LBB0_1221
	s_barrier
	s_branch .LBB0_1221
